# gates stage: the twelve bias loads issued before the stage barrier together with the weight-fragment loads
# baseline (speedup 1.0000x reference)
; #define LAS __attribute__((address_space(3)))
; __device__ __forceinline__ float bf2f(unsigned short b) { return __uint_as_float(((unsigned)b) << 16); }
; __device__ __forceinline__ unsigned short f2bf(float f) { return (unsigned short)(pg8::cvt_pk_bf16(f, 0.f) & 0xffffu); }
; __device__ __forceinline__ float softplusf_(float x) { const float e = __expf(-fabsf(x)); const float lg = (e < 0.03f) ? e * (1.0f - e * (0.5f - e * (0.33333334f - 0.25f * e))) : __logf(1.0f + e); return fmaxf(x, 0.f) + lg; }
; #define MFMA16(a, b, c) __builtin_amdgcn_mfma_f32_16x16x32_bf16((a), (b), (c), 0, 0, 0)
; __device__ __forceinline__ void mixer_pre_item(int item, const float* const* in, int l, unsigned char* ws, LAS unsigned char* lds, int tid, int lane, int wave) {
;     ...
; #pragma unroll 8
;         for (int i = 0; i < 16; ++i) { const float xc = bf2f(STGL[(t0 + i + 3) * 256 + ch]); const float xr = w0 * xm3 + w1 * xm2 + w2 * xm1 + w3 * xc + bb;
;             XRF[(t0 + i) * 256 + ch] = xr; XRB[(t0 + i) * 264 + ch] = f2bf(xr); xm3 = xm2; xm2 = xm1; xm1 = xc; }
;     }
;     __syncthreads();
;     {
;         const int hb = wave & 3, mf = wave >> 2, fr = lane & 15, q = lane >> 4;
;         const bf16_t* WTa = (const bf16_t*)(ws + WS_W + (size_t)l * W_LAYER + O_LRU) + hb * 4096;
;         const bf16_t* WTx = WTa + 16384;
;         f32x4 aa[4], ax[4];
; #pragma unroll
;         for (int nf = 0; nf < 4; ++nf) { aa[nf] = (f32x4){0.f, 0.f, 0.f, 0.f}; ax[nf] = (f32x4){0.f, 0.f, 0.f, 0.f}; }
; #pragma unroll
;         for (int ks = 0; ks < 2; ++ks) {
;             const bf16x8 A = *(const LAS bf16x8*)(XRB + (16 * mf + fr) * 264 + 64 * hb + 32 * ks + 8 * q);
; #pragma unroll
;             for (int nf = 0; nf < 4; ++nf) {
;                 const bf16x8 Ba = *(const bf16x8*)(WTa + (16 * nf + fr) * 64 + 32 * ks + 8 * q), Bx = *(const bf16x8*)(WTx + (16 * nf + fr) * 64 + 32 * ks + 8 * q);
;                 aa[nf] = MFMA16(A, Ba, aa[nf]); ax[nf] = MFMA16(A, Bx, ax[nf]); }
;         }
; #pragma unroll
;         for (int nf = 0; nf < 4; ++nf) {
;             const int ch = 64 * hb + 16 * nf + fr;
;             const float ba = in[11][l * 256 + ch], bx = in[13][l * 256 + ch], sp = softplusf_(-in[14][l * 256 + ch]);
.LBB0_640:
	v_add_u32_e32 v12, 0, v8
	ds_read_u16 v13, v12
	v_mul_f32_e32 v14, v5, v10
	v_fmac_f32_e32 v14, v4, v11
	v_fmac_f32_e32 v14, v6, v9
	v_add_u32_e32 v15, 0, v2
	s_waitcnt lgkmcnt(0)
	v_lshlrev_b32_e32 v13, 16, v13
	v_fmac_f32_e32 v14, v7, v13
	s_waitcnt vmcnt(0)
	v_add_f32_e32 v11, v0, v14
	v_add_u32_e32 v14, 0, v3
	v_add_u32_e32 v16, 0x14600, v15
	ds_write_b32 v14, v11
	v_cvt_pk_bf16_f32 v11, v11, v1
	ds_write_b16 v16, v11
	ds_read_u16 v11, v12 offset:512
	v_mul_f32_e32 v16, v5, v9
	v_fmac_f32_e32 v16, v4, v10
	v_fmac_f32_e32 v16, v6, v13
	s_add_i32 s20, s20, -8
	s_waitcnt lgkmcnt(0)
	v_lshlrev_b32_e32 v11, 16, v11
	v_fmac_f32_e32 v16, v7, v11
	v_add_f32_e32 v10, v0, v16
	v_add_u32_e32 v16, 0x14810, v15
	ds_write_b32 v14, v10 offset:1024
	v_cvt_pk_bf16_f32 v10, v10, v1
	ds_write_b16 v16, v10
	ds_read_u16 v10, v12 offset:1024
	v_mul_f32_e32 v16, v5, v13
	v_fmac_f32_e32 v16, v4, v9
	v_fmac_f32_e32 v16, v6, v11
	v_add_u32_e32 v2, 0x1080, v2
	s_waitcnt lgkmcnt(0)
	v_lshlrev_b32_e32 v10, 16, v10
	v_fmac_f32_e32 v16, v7, v10
	v_add_f32_e32 v9, v0, v16
	v_add_u32_e32 v16, 0x14a20, v15
	ds_write_b32 v14, v9 offset:2048
	v_cvt_pk_bf16_f32 v9, v9, v1
	ds_write_b16 v16, v9
	ds_read_u16 v9, v12 offset:1536
	v_mul_f32_e32 v16, v5, v11
	v_fmac_f32_e32 v16, v4, v13
	v_fmac_f32_e32 v16, v6, v10
	v_add_u32_e32 v3, 0x2000, v3
	s_waitcnt lgkmcnt(0)
	v_lshlrev_b32_e32 v9, 16, v9
	v_fmac_f32_e32 v16, v7, v9
	v_add_f32_e32 v13, v0, v16
	v_add_u32_e32 v16, 0x14c30, v15
	ds_write_b32 v14, v13 offset:3072
	v_cvt_pk_bf16_f32 v13, v13, v1
	ds_write_b16 v16, v13
	ds_read_u16 v13, v12 offset:2048
	v_mul_f32_e32 v16, v5, v10
	v_fmac_f32_e32 v16, v4, v11
	v_fmac_f32_e32 v16, v6, v9
	v_add_u32_e32 v8, 0x1000, v8
	s_waitcnt lgkmcnt(0)
	v_lshlrev_b32_e32 v13, 16, v13
	v_fmac_f32_e32 v16, v7, v13
	v_add_f32_e32 v11, v0, v16
	v_add_u32_e32 v16, 0x14e40, v15
	ds_write_b32 v14, v11 offset:4096
	v_cvt_pk_bf16_f32 v11, v11, v1
	ds_write_b16 v16, v11
	ds_read_u16 v11, v12 offset:2560
	v_mul_f32_e32 v16, v5, v9
	v_fmac_f32_e32 v16, v4, v10
	v_fmac_f32_e32 v16, v6, v13
	s_cmp_eq_u32 s20, 0
	s_waitcnt lgkmcnt(0)
	v_lshlrev_b32_e32 v11, 16, v11
	v_fmac_f32_e32 v16, v7, v11
	v_add_f32_e32 v10, v0, v16
	v_add_u32_e32 v16, 0x15050, v15
	ds_write_b32 v14, v10 offset:5120
	v_cvt_pk_bf16_f32 v10, v10, v1
	ds_write_b16 v16, v10
	ds_read_u16 v10, v12 offset:3072
	v_mul_f32_e32 v16, v5, v13
	v_fmac_f32_e32 v16, v4, v9
	v_fmac_f32_e32 v16, v6, v11
	s_waitcnt lgkmcnt(0)
	v_lshlrev_b32_e32 v10, 16, v10
	v_fmac_f32_e32 v16, v7, v10
	v_add_f32_e32 v9, v0, v16
	v_add_u32_e32 v16, 0x15260, v15
	ds_write_b32 v14, v9 offset:6144
	v_cvt_pk_bf16_f32 v9, v9, v1
	ds_write_b16 v16, v9
	ds_read_u16 v9, v12 offset:3584
	v_mul_f32_e32 v12, v5, v11
	v_fmac_f32_e32 v12, v4, v13
	v_fmac_f32_e32 v12, v6, v10
	v_add_u32_e32 v13, 0x15470, v15
	s_waitcnt lgkmcnt(0)
	v_lshlrev_b32_e32 v9, 16, v9
	v_fmac_f32_e32 v12, v7, v9
	v_add_f32_e32 v12, v0, v12
	ds_write_b32 v14, v12 offset:7168
	v_cvt_pk_bf16_f32 v12, v12, v1
	ds_write_b16 v13, v12
	s_cbranch_scc0 .LBB0_640
	s_bfe_u32 s20, s15, 0x20006
	s_lshl_b32 s21, s20, 13
	s_add_u32 s30, s6, s21
	s_addc_u32 s31, s7, 0
	s_ashr_i32 s15, s15, 4
	v_bfi_b32 v0, -16, s15, v34
	s_movk_i32 s21, 0x210
	v_mul_lo_u32 v2, v0, s21
	s_lshl_b32 s21, s20, 7
	s_add_i32 s21, s21, 0
	v_and_b32_e32 v62, 15, v34
	s_add_i32 s21, s21, 0x14600
	v_and_b32_e32 v0, 48, v35
	v_add3_u32 v48, s21, v2, v0
	v_lshl_add_u64 v[30:31], s[30:31], 0, v[0:1]
	s_mov_b64 s[30:31], 0x8000
	v_lshlrev_b32_e32 v0, 7, v62
	v_lshl_add_u64 v[32:33], v[30:31], 0, s[30:31]
	v_or_b32_e32 v56, 0x1000, v0
	v_mov_b32_e32 v57, v1
	v_lshl_add_u64 v[52:53], v[30:31], 0, v[0:1]
	v_lshl_add_u64 v[54:55], v[32:33], 0, v[0:1]
	v_lshl_add_u64 v[22:23], v[30:31], 0, v[56:57]
	v_lshl_add_u64 v[26:27], v[32:33], 0, v[56:57]
	global_load_dwordx4 v[108:111], v[52:53], off offset:2048
	global_load_dwordx4 v[112:115], v[22:23], off
	global_load_dwordx4 v[116:119], v[26:27], off
	global_load_dwordx4 v[120:123], v[52:53], off
	global_load_dwordx4 v[124:127], v[54:55], off
	global_load_dwordx4 v[128:131], v[54:55], off offset:2048
	global_load_dwordx4 v[132:135], v[22:23], off offset:2048
	global_load_dwordx4 v[136:139], v[26:27], off offset:2048
	global_load_dwordx4 v[140:143], v[52:53], off offset:64
	global_load_dwordx4 v[144:147], v[54:55], off offset:64
	global_load_dwordx4 v[148:151], v[52:53], off offset:2112
	global_load_dwordx4 v[152:155], v[54:55], off offset:2112
	global_load_dwordx4 v[168:171], v[22:23], off offset:64
	global_load_dwordx4 v[172:175], v[26:27], off offset:64
	global_load_dwordx4 v[176:179], v[26:27], off offset:2112
	global_load_dwordx4 v[180:183], v[22:23], off offset:2112
	v_lshl_or_b32 v81, s20, 6, v62
	v_or_b32_e32 v82, s1, v81
	v_mov_b32_e32 v83, 0
	v_lshlrev_b64 v[82:83], 2, v[82:83]
	v_readlane_b32 s100, v248, 51
	v_readlane_b32 s101, v248, 52
	s_nop 1
	v_lshl_add_u64 v[84:85], s[100:101], 0, v[82:83]
	global_load_dword v78, v[84:85], off
	global_load_dword v64, v[84:85], off offset:64
	global_load_dword v65, v[84:85], off offset:128
	global_load_dword v66, v[84:85], off offset:192
	v_readlane_b32 s100, v248, 55
	v_readlane_b32 s101, v248, 56
	s_nop 1
	v_lshl_add_u64 v[86:87], s[100:101], 0, v[82:83]
	global_load_dword v80, v[86:87], off
	global_load_dword v67, v[86:87], off offset:64
	global_load_dword v68, v[86:87], off offset:128
	global_load_dword v69, v[86:87], off offset:192
	v_readlane_b32 s100, v248, 57
	v_readlane_b32 s101, v248, 58
	s_nop 1
	v_lshl_add_u64 v[88:89], s[100:101], 0, v[82:83]
	global_load_dword v79, v[88:89], off
	global_load_dword v70, v[88:89], off offset:64
	global_load_dword v71, v[88:89], off offset:128
	global_load_dword v72, v[88:89], off offset:192
	s_waitcnt lgkmcnt(0)
	s_barrier
; #define LAS __attribute__((address_space(3)))
; __device__ __forceinline__ float sigmoidf_(float x) { return __builtin_amdgcn_rcpf(1.0f + __expf(-x)); }
; __device__ __forceinline__ float softplusf_(float x) { const float e = __expf(-fabsf(x)); const float lg = (e < 0.03f) ? e * (1.0f - e * (0.5f - e * (0.33333334f - 0.25f * e))) : __logf(1.0f + e); return fmaxf(x, 0.f) + lg; }
; #define MFMA16(a, b, c) __builtin_amdgcn_mfma_f32_16x16x32_bf16((a), (b), (c), 0, 0, 0)
; __device__ __forceinline__ void mixer_pre_item(int item, const float* const* in, int l, unsigned char* ws, LAS unsigned char* lds, int tid, int lane, int wave) {
;     ...
;         for (int ks = 0; ks < 2; ++ks) {
;             const bf16x8 A = *(const LAS bf16x8*)(XRB + (16 * mf + fr) * 264 + 64 * hb + 32 * ks + 8 * q);
; #pragma unroll
;             for (int nf = 0; nf < 4; ++nf) {
;                 const bf16x8 Ba = *(const bf16x8*)(WTa + (16 * nf + fr) * 64 + 32 * ks + 8 * q), Bx = *(const bf16x8*)(WTx + (16 * nf + fr) * 64 + 32 * ks + 8 * q);
;                 aa[nf] = MFMA16(A, Ba, aa[nf]); ax[nf] = MFMA16(A, Bx, ax[nf]); }
;         }
; #pragma unroll
;         for (int nf = 0; nf < 4; ++nf) {
;             const int ch = 64 * hb + 16 * nf + fr;
;             const float ba = in[11][l * 256 + ch], bx = in[13][l * 256 + ch], sp = softplusf_(-in[14][l * 256 + ch]);
; #pragma unroll
;             for (int jj = 0; jj < 4; ++jj) { const int tok = 16 * mf + 4 * q + jj;
;                 const float r = sigmoidf_(aa[nf][jj] + ba), ig = sigmoidf_(ax[nf][jj] + bx), la = -8.0f * r * sp, a = __expf(la), x2 = 2.0f * la;
;                 const float om = (x2 > -0.25f) ? -x2 * (1.0f + x2 * (0.5f + x2 * (0.16666667f + x2 * (0.041666668f + x2 * (0.008333334f + x2 * 0.0013888889f))))) : 1.0f - a * a;
;                 const float mult = sqrtf(om);
;                 const float xr = XRF[tok * 256 + ch]; AF[tok * 256 + ch] = a; XRF[tok * 256 + ch] = mult * ig * xr; }
	ds_read_b128 v[2:5], v48
	ds_read_b128 v[48:51], v48 offset:64
	s_mov_b64 s[30:31], 0x8040
	v_lshl_add_u64 v[58:59], v[30:31], 0, 64
	v_lshl_add_u64 v[60:61], v[30:31], 0, s[30:31]
	v_readlane_b32 s48, v248, 55
	v_readlane_b32 s49, v248, 56
	v_readlane_b32 s50, v248, 57
	v_readlane_b32 s51, v248, 58
	v_readlane_b32 s52, v248, 59
	v_readlane_b32 s53, v248, 60
	v_readlane_b32 s54, v248, 61
	v_readlane_b32 s55, v248, 62
	v_readlane_b32 s56, v248, 63
	v_readlane_b32 s57, v250, 0
	v_readlane_b32 s58, v250, 1
	v_readlane_b32 s59, v250, 2
	v_readlane_b32 s60, v250, 3
	v_readlane_b32 s61, v250, 4
	v_readlane_b32 s62, v250, 5
	v_readlane_b32 s63, v250, 6
	s_waitcnt vmcnt(27) lgkmcnt(1)
	v_mfma_f32_16x16x32_bf16 v[14:17], v[2:5], v[108:111], 0
	s_waitcnt vmcnt(26)
	v_mfma_f32_16x16x32_bf16 v[36:39], v[2:5], v[112:115], 0
	s_waitcnt vmcnt(25)
	v_mfma_f32_16x16x32_bf16 v[40:43], v[2:5], v[116:119], 0
	s_waitcnt vmcnt(24)
	v_mfma_f32_16x16x32_bf16 v[6:9], v[2:5], v[120:123], 0
	s_waitcnt vmcnt(23)
	v_mfma_f32_16x16x32_bf16 v[10:13], v[2:5], v[124:127], 0
	s_waitcnt vmcnt(22)
	v_mfma_f32_16x16x32_bf16 v[18:21], v[2:5], v[128:131], 0
	s_waitcnt vmcnt(21)
	v_mfma_f32_16x16x32_bf16 v[44:47], v[2:5], v[132:135], 0
	s_waitcnt vmcnt(20)
	v_mfma_f32_16x16x32_bf16 v[2:5], v[2:5], v[136:139], 0
	s_waitcnt vmcnt(19) lgkmcnt(0)
	v_mfma_f32_16x16x32_bf16 v[30:33], v[48:51], v[140:143], v[6:9]
	s_waitcnt vmcnt(18)
	v_mfma_f32_16x16x32_bf16 v[26:29], v[48:51], v[144:147], v[10:13]
	s_waitcnt vmcnt(17)
	v_mfma_f32_16x16x32_bf16 v[22:25], v[48:51], v[148:151], v[14:17]
	s_waitcnt vmcnt(16)
	v_mfma_f32_16x16x32_bf16 v[18:21], v[48:51], v[152:155], v[18:21]
	s_waitcnt vmcnt(15)
	v_mfma_f32_16x16x32_bf16 v[14:17], v[48:51], v[168:171], v[36:39]
	s_waitcnt vmcnt(14)
	v_mfma_f32_16x16x32_bf16 v[10:13], v[48:51], v[172:175], v[40:43]
	s_waitcnt vmcnt(13)
	v_mfma_f32_16x16x32_bf16 v[2:5], v[48:51], v[176:179], v[2:5]
	v_lshl_or_b32 v36, s20, 6, v62
	v_or_b32_e32 v0, s1, v36
	v_readlane_b32 s20, v248, 51
	v_lshlrev_b64 v[38:39], 2, v[0:1]
	v_readlane_b32 s21, v248, 52
	s_waitcnt vmcnt(12)
	v_mfma_f32_16x16x32_bf16 v[6:9], v[48:51], v[180:183], v[44:47]
	s_nop 0
	v_lshl_add_u64 v[40:41], s[20:21], 0, v[38:39]
	s_waitcnt vmcnt(0)
	v_mov_b32_e32 v37, v78
	v_lshl_add_u64 v[40:41], s[48:49], 0, v[38:39]
	v_lshl_add_u64 v[38:39], s[50:51], 0, v[38:39]
	v_mov_b32_e32 v38, v79
	s_mov_b32 s20, 0xbfb8aa3b
	v_mov_b32_e32 v0, v80
	s_waitcnt vmcnt(1)
	v_mul_f32_e64 v39, |v38|, s20
	v_exp_f32_e32 v40, v39
	s_mov_b32 s20, 0x3cf5c28f
	v_cmp_ngt_f32_e32 vcc, s20, v40
	s_and_saveexec_b64 s[20:21], vcc
	v_readlane_b32 s94, v250, 11
	s_xor_b64 s[20:21], exec, s[20:21]
	v_readlane_b32 s95, v250, 12
	v_readlane_b32 s33, v250, 22
	s_movk_i32 s45, 0x1ff
	s_cbranch_execz .LBB0_643
	v_add_f32_e32 v39, 1.0, v40
	s_mov_b32 s30, 0x800000
	v_cmp_gt_f32_e32 vcc, s30, v39
	s_mov_b32 s30, 0x3f317217
	s_nop 0
	v_cndmask_b32_e64 v40, 0, 32, vcc
	v_ldexp_f32 v39, v39, v40
	v_log_f32_e32 v39, v39
	s_nop 0
	v_mul_f32_e32 v40, 0x3f317217, v39
	v_fma_f32 v40, v39, s30, -v40
	v_fmac_f32_e32 v40, 0x3377d1cf, v39
	s_mov_b32 s30, 0x7f800000
	v_fmac_f32_e32 v40, 0x3f317217, v39
	v_cmp_lt_f32_e64 s[40:41], |v39|, s30
	s_nop 1
	v_cndmask_b32_e64 v39, v39, v40, s[40:41]
	v_cndmask_b32_e32 v40, 0, v232, vcc
	v_sub_f32_e32 v39, v39, v40
.LBB0_643:
	s_andn2_saveexec_b64 s[20:21], s[20:21]
	v_fmamk_f32 v39, v40, 0xbe800000, v228
	v_fma_f32 v39, -v40, v39, 0.5
	v_fma_f32 v39, -v40, v39, 1.0
	v_mul_f32_e32 v39, v40, v39
	s_or_b64 exec, exec, s[20:21]
	v_add_f32_e32 v30, v30, v37
	v_mul_f32_e32 v30, 0xbfb8aa3b, v30
	v_exp_f32_e32 v30, v30
	s_mov_b32 s20, 0xbe800000
	v_add_f32_e32 v30, 1.0, v30
	v_rcp_f32_e32 v40, v30
	v_max_f32_e64 v30, -v38, -v38
	v_max_f32_e32 v30, 0, v30
	v_add_f32_e32 v30, v30, v39
	v_mul_f32_e32 v38, 0xc1000000, v40
	v_mul_f32_e32 v39, v38, v30
	v_mul_f32_e32 v38, 0x3fb8aa3b, v39
	v_exp_f32_e32 v38, v38
	v_add_f32_e32 v40, v39, v39
	v_cmp_nlt_f32_e32 vcc, s20, v40
	s_and_saveexec_b64 s[20:21], vcc
	s_xor_b64 s[20:21], exec, s[20:21]
	v_fma_f32 v39, -v38, v38, 1.0
	s_andn2_saveexec_b64 s[20:21], s[20:21]
	v_fmamk_f32 v39, v40, 0x3ab60b61, v229
	v_fmaak_f32 v39, v40, v39, 0x3d2aaaab
	v_fmaak_f32 v39, v40, v39, 0x3e2aaaab
	v_fma_f32 v39, v40, v39, 0.5
	v_fma_f32 v39, v40, v39, 1.0
	v_mul_f32_e64 v39, v39, -v40
	s_or_b64 exec, exec, s[20:21]
	s_waitcnt vmcnt(0)
	v_add_f32_e32 v26, v26, v0
	v_mul_f32_e32 v26, 0xbfb8aa3b, v26
	v_mul_f32_e32 v40, 0x4f800000, v39
	v_cmp_gt_f32_e32 vcc, s26, v39
	v_exp_f32_e32 v26, v26
	v_add_f32_e32 v31, v31, v37
	v_cndmask_b32_e32 v39, v39, v40, vcc
	v_sqrt_f32_e32 v40, v39
	v_add_f32_e32 v26, 1.0, v26
	v_rcp_f32_e32 v41, v26
	v_mul_f32_e32 v31, 0xbfb8aa3b, v31
	v_add_u32_e32 v26, -1, v40
	v_fma_f32 v42, -v26, v40, v39
	v_cmp_ge_f32_e64 s[40:41], 0, v42
	v_add_u32_e32 v42, 1, v40
	v_exp_f32_e32 v31, v31
	v_cndmask_b32_e64 v26, v40, v26, s[40:41]
	v_fma_f32 v40, -v42, v40, v39
	v_cmp_lt_f32_e64 s[40:41], 0, v40
	v_lshrrev_b32_e32 v35, 4, v35
	s_and_b32 s15, s15, -16
	v_cndmask_b32_e64 v26, v26, v42, s[40:41]
	v_mul_f32_e32 v40, 0x37800000, v26
	v_cndmask_b32_e32 v40, v26, v40, vcc
	v_lshlrev_b32_e32 v26, 10, v35
	v_add_f32_e32 v31, 1.0, v31
	v_lshl_or_b32 v26, s15, 8, v26
	v_rcp_f32_e32 v31, v31
	v_or_b32_e32 v35, v26, v36
	v_lshl_add_u32 v35, v35, 2, 0
	ds_read_b32 v42, v35 offset:17920
	v_cmp_class_f32_e32 vcc, v39, v230
	v_mul_f32_e32 v31, 0xc1000000, v31
	s_mov_b32 s15, 0xbe800000
	v_cndmask_b32_e32 v39, v40, v39, vcc
	v_mul_f32_e32 v40, v31, v30
	v_mul_f32_e32 v31, 0x3fb8aa3b, v40
	v_mul_f32_e32 v39, v41, v39
	v_exp_f32_e32 v31, v31
	s_waitcnt lgkmcnt(0)
; __device__ __forceinline__ float sigmoidf_(float x) { return __builtin_amdgcn_rcpf(1.0f + __expf(-x)); }
; __device__ __forceinline__ float softplusf_(float x) { const float e = __expf(-fabsf(x)); const float lg = (e < 0.03f) ? e * (1.0f - e * (0.5f - e * (0.33333334f - 0.25f * e))) : __logf(1.0f + e); return fmaxf(x, 0.f) + lg; }
; __device__ __forceinline__ void mixer_pre_item(int item, const float* const* in, int l, unsigned char* ws, LAS unsigned char* lds, int tid, int lane, int wave) {
;     ...
;         for (int nf = 0; nf < 4; ++nf) {
;             const int ch = 64 * hb + 16 * nf + fr;
;             const float ba = in[11][l * 256 + ch], bx = in[13][l * 256 + ch], sp = softplusf_(-in[14][l * 256 + ch]);
; #pragma unroll
;             for (int jj = 0; jj < 4; ++jj) { const int tok = 16 * mf + 4 * q + jj;
;                 const float r = sigmoidf_(aa[nf][jj] + ba), ig = sigmoidf_(ax[nf][jj] + bx), la = -8.0f * r * sp, a = __expf(la), x2 = 2.0f * la;
;                 const float om = (x2 > -0.25f) ? -x2 * (1.0f + x2 * (0.5f + x2 * (0.16666667f + x2 * (0.041666668f + x2 * (0.008333334f + x2 * 0.0013888889f))))) : 1.0f - a * a;
;                 const float mult = sqrtf(om);
;                 const float xr = XRF[tok * 256 + ch]; AF[tok * 256 + ch] = a; XRF[tok * 256 + ch] = mult * ig * xr; }
	v_mul_f32_e32 v39, v42, v39
	ds_write2st64_b32 v35, v39, v38 offset0:70 offset1:198
	v_add_f32_e32 v38, v40, v40
	v_cmp_nlt_f32_e32 vcc, s15, v38
	s_and_saveexec_b64 s[20:21], vcc
	s_xor_b64 s[20:21], exec, s[20:21]
	v_fma_f32 v35, -v31, v31, 1.0
	s_andn2_saveexec_b64 s[20:21], s[20:21]
	v_fmamk_f32 v35, v38, 0x3ab60b61, v229
	v_fmaak_f32 v35, v38, v35, 0x3d2aaaab
	v_fmaak_f32 v35, v38, v35, 0x3e2aaaab
	v_fma_f32 v35, v38, v35, 0.5
	v_fma_f32 v35, v38, v35, 1.0
	v_mul_f32_e64 v35, v35, -v38
	s_or_b64 exec, exec, s[20:21]
	v_mul_f32_e32 v38, 0x4f800000, v35
	v_cmp_gt_f32_e32 vcc, s26, v35
	v_add_f32_e32 v27, v27, v0
	v_mul_f32_e32 v27, 0xbfb8aa3b, v27
	v_cndmask_b32_e32 v35, v35, v38, vcc
	v_sqrt_f32_e32 v38, v35
	v_add_f32_e32 v32, v32, v37
	v_exp_f32_e32 v27, v27
	v_mul_f32_e32 v32, 0xbfb8aa3b, v32
	v_add_u32_e32 v39, -1, v38
	v_fma_f32 v40, -v39, v38, v35
	v_cmp_ge_f32_e64 s[40:41], 0, v40
	v_add_u32_e32 v40, 1, v38
	v_add_u32_e32 v26, v26, v36
	v_cndmask_b32_e64 v39, v38, v39, s[40:41]
	v_fma_f32 v38, -v40, v38, v35
	v_cmp_lt_f32_e64 s[40:41], 0, v38
	v_add_f32_e32 v27, 1.0, v27
	v_rcp_f32_e32 v27, v27
	v_cndmask_b32_e64 v38, v39, v40, s[40:41]
	v_mul_f32_e32 v39, 0x37800000, v38
	v_cndmask_b32_e32 v38, v38, v39, vcc
	v_exp_f32_e32 v39, v32
	v_lshl_add_u32 v32, v26, 2, 0
	ds_read_b32 v26, v32 offset:18944
	v_cmp_class_f32_e32 vcc, v35, v230
	v_add_f32_e32 v39, 1.0, v39
	v_rcp_f32_e32 v39, v39
	v_cndmask_b32_e32 v35, v38, v35, vcc
	v_mul_f32_e32 v27, v27, v35
	s_waitcnt lgkmcnt(0)
	v_mul_f32_e32 v27, v26, v27
	v_mul_f32_e32 v26, 0xc1000000, v39
	v_mul_f32_e32 v35, v26, v30
	v_mul_f32_e32 v26, 0x3fb8aa3b, v35
	v_exp_f32_e32 v26, v26
	ds_write2st64_b32 v32, v27, v31 offset0:74 offset1:202
	v_add_f32_e32 v31, v35, v35
	v_cmp_nlt_f32_e32 vcc, s15, v31
	s_and_saveexec_b64 s[20:21], vcc
	s_xor_b64 s[20:21], exec, s[20:21]
	v_fma_f32 v27, -v26, v26, 1.0
	s_andn2_saveexec_b64 s[20:21], s[20:21]
	v_fmamk_f32 v27, v31, 0x3ab60b61, v229
	v_fmaak_f32 v27, v31, v27, 0x3d2aaaab
	v_fmaak_f32 v27, v31, v27, 0x3e2aaaab
	v_fma_f32 v27, v31, v27, 0.5
	v_fma_f32 v27, v31, v27, 1.0
	v_mul_f32_e64 v27, v27, -v31
	s_or_b64 exec, exec, s[20:21]
	v_mul_f32_e32 v31, 0x4f800000, v27
	v_cmp_gt_f32_e32 vcc, s26, v27
	v_add_f32_e32 v28, v28, v0
	v_mul_f32_e32 v28, 0xbfb8aa3b, v28
	v_cndmask_b32_e32 v27, v27, v31, vcc
	v_sqrt_f32_e32 v31, v27
	v_add_f32_e32 v33, v33, v37
	v_exp_f32_e32 v28, v28
	v_mul_f32_e32 v33, 0xbfb8aa3b, v33
	v_add_u32_e32 v35, -1, v31
	v_fma_f32 v38, -v35, v31, v27
	v_cmp_ge_f32_e64 s[40:41], 0, v38
	v_add_u32_e32 v38, 1, v31
	v_exp_f32_e32 v33, v33
	v_cndmask_b32_e64 v35, v31, v35, s[40:41]
	v_fma_f32 v31, -v38, v31, v27
	v_cmp_lt_f32_e64 s[40:41], 0, v31
	v_add_f32_e32 v28, 1.0, v28
	v_rcp_f32_e32 v28, v28
	v_cndmask_b32_e64 v31, v35, v38, s[40:41]
	v_mul_f32_e32 v35, 0x37800000, v31
	v_cndmask_b32_e32 v31, v31, v35, vcc
	ds_read_b32 v35, v32 offset:19968
	v_add_f32_e32 v33, 1.0, v33
	v_rcp_f32_e32 v33, v33
	v_cmp_class_f32_e32 vcc, v27, v230
	s_nop 1
	v_cndmask_b32_e32 v27, v31, v27, vcc
	v_mul_f32_e32 v27, v28, v27
	s_waitcnt lgkmcnt(0)
	v_mul_f32_e32 v28, v35, v27
	v_mul_f32_e32 v27, 0xc1000000, v33
	v_mul_f32_e32 v30, v27, v30
	v_mul_f32_e32 v27, 0x3fb8aa3b, v30
	v_exp_f32_e32 v27, v27
	ds_write2st64_b32 v32, v28, v26 offset0:78 offset1:206
	v_add_f32_e32 v28, v30, v30
	v_cmp_nlt_f32_e32 vcc, s15, v28
	s_and_saveexec_b64 s[20:21], vcc
	s_xor_b64 s[20:21], exec, s[20:21]
	v_fma_f32 v26, -v27, v27, 1.0
	s_andn2_saveexec_b64 s[20:21], s[20:21]
	v_fmamk_f32 v26, v28, 0x3ab60b61, v229
	v_fmaak_f32 v26, v28, v26, 0x3d2aaaab
	v_fmaak_f32 v26, v28, v26, 0x3e2aaaab
	v_fma_f32 v26, v28, v26, 0.5
	v_fma_f32 v26, v28, v26, 1.0
	v_mul_f32_e64 v26, v26, -v28
	s_or_b64 exec, exec, s[20:21]
	v_cmp_gt_f32_e32 vcc, s26, v26
	v_mul_f32_e32 v28, 0x4f800000, v26
	v_add_f32_e32 v0, v29, v0
	v_cndmask_b32_e32 v26, v26, v28, vcc
	v_sqrt_f32_e32 v28, v26
	v_mul_f32_e32 v0, 0xbfb8aa3b, v0
	v_exp_f32_e32 v0, v0
	v_readlane_b32 s20, v248, 51
	v_add_u32_e32 v29, -1, v28
	v_fma_f32 v30, -v29, v28, v26
	v_cmp_ge_f32_e64 s[40:41], 0, v30
	v_add_u32_e32 v30, 1, v28
	v_add_f32_e32 v0, 1.0, v0
	v_cndmask_b32_e64 v29, v28, v29, s[40:41]
	v_fma_f32 v28, -v30, v28, v26
	v_cmp_lt_f32_e64 s[40:41], 0, v28
	v_rcp_f32_e32 v0, v0
	v_readlane_b32 s48, v248, 55
	v_cndmask_b32_e64 v28, v29, v30, s[40:41]
	v_mul_f32_e32 v29, 0x37800000, v28
	v_cndmask_b32_e32 v28, v28, v29, vcc
	v_cmp_class_f32_e32 vcc, v26, v230
	v_readlane_b32 s21, v248, 52
	v_readlane_b32 s49, v248, 56
	v_cndmask_b32_e32 v26, v28, v26, vcc
	ds_read_b32 v28, v32 offset:20992
	v_mul_f32_e32 v0, v0, v26
	v_readlane_b32 s50, v248, 57
	v_readlane_b32 s51, v248, 58
	s_mov_b32 s15, 0xbfb8aa3b
	s_waitcnt lgkmcnt(0)
	v_mul_f32_e32 v0, v28, v0
	ds_write2st64_b32 v32, v0, v27 offset0:82 offset1:210
	v_add_u32_e32 v0, s1, v36
	v_lshlrev_b64 v[26:27], 2, v[0:1]
	v_lshl_add_u64 v[28:29], s[20:21], 0, v[26:27]
	v_lshl_add_u64 v[30:31], s[48:49], 0, v[26:27]
	v_lshl_add_u64 v[26:27], s[50:51], 0, v[26:27]
	v_mov_b32_e32 v35, v70
	v_mov_b32_e32 v33, v64
	v_mov_b32_e32 v0, v67
	v_readlane_b32 s52, v248, 59
	v_readlane_b32 s53, v248, 60
	v_readlane_b32 s54, v248, 61
	v_readlane_b32 s55, v248, 62
	v_readlane_b32 s56, v248, 63
	v_readlane_b32 s57, v250, 0
	v_readlane_b32 s58, v250, 1
	v_readlane_b32 s59, v250, 2
	v_readlane_b32 s60, v250, 3
	v_readlane_b32 s61, v250, 4
	v_readlane_b32 s62, v250, 5
	v_readlane_b32 s63, v250, 6
	s_waitcnt vmcnt(2)
	v_mul_f32_e64 v36, |v35|, s15
	v_exp_f32_e32 v36, v36
	s_mov_b32 s15, 0x3cf5c28f
	v_cmp_ngt_f32_e32 vcc, s15, v36
	s_and_saveexec_b64 s[20:21], vcc
	s_xor_b64 s[20:21], exec, s[20:21]
	s_cbranch_execz .LBB0_663
	v_add_f32_e32 v36, 1.0, v36
	s_mov_b32 s15, 0x800000
	v_cmp_gt_f32_e32 vcc, s15, v36
	s_mov_b32 s15, 0x3f317217
	s_nop 0
	v_cndmask_b32_e64 v37, 0, 32, vcc
	v_ldexp_f32 v36, v36, v37
	v_log_f32_e32 v36, v36
	s_nop 0
	v_mul_f32_e32 v37, 0x3f317217, v36
	v_fma_f32 v37, v36, s15, -v37
	v_fmac_f32_e32 v37, 0x3377d1cf, v36
	s_mov_b32 s15, 0x7f800000
	v_fmac_f32_e32 v37, 0x3f317217, v36
	v_cmp_lt_f32_e64 s[40:41], |v36|, s15
	s_nop 1
	v_cndmask_b32_e64 v36, v36, v37, s[40:41]
	v_cndmask_b32_e32 v37, 0, v232, vcc
	v_sub_f32_e32 v37, v36, v37
